# v10 + barrier pollers spread over the 16 release words (bx & 15)
# speedup vs baseline: 1.0007x; 1.0007x over previous
; __device__ __forceinline__ unsigned xb_ld(unsigned* p)              { return __hip_atomic_load(p, __ATOMIC_RELAXED, __HIP_MEMORY_SCOPE_AGENT); }
; __device__ __forceinline__ unsigned xb_add(unsigned* p, unsigned v) { return __hip_atomic_fetch_add(p, v, __ATOMIC_RELAXED, __HIP_MEMORY_SCOPE_AGENT); }
; #define XB_SPIN(cond, bar) do { unsigned _sp = 0; while (cond) { __builtin_amdgcn_s_sleep(1); \
;     if ((++_sp & 255u) == 0u) { if (xb_ld(&(bar)[XB_TMO])) break; if (_sp > XB_SPIN_CAP) { atomicAdd(&(bar)[XB_TMO], 1u); break; } } } } while (0)
; __device__ __forceinline__ void xcd_barrier(const XcdBarrier& b) {
;     ...
;         const unsigned old = xb_add(&bar[XB_XSUB(b.x)], 1u);
;         const unsigned gen = old / nloc;
;         if (old + 1u == (gen + 1u) * nloc) {
;             __builtin_amdgcn_fence(__ATOMIC_RELEASE, "agent");
;             asm volatile("s_waitcnt vmcnt(0)" ::: "memory");
;             const unsigned og = xb_add(&bar[XB_TOP], 1u);
;             const unsigned tg = og / nx;
;             if (og + 1u == (tg + 1u) * nx) xb_add(&bar[XB_TOPGEN], 1u);
;             else XB_SPIN(xb_ld(&bar[XB_TOPGEN]) == tg, bar);
;             __builtin_amdgcn_fence(__ATOMIC_ACQUIRE, "agent");
;             xb_add(&bar[XB_XGEN(b.x)], 1u);
;             asm volatile("s_waitcnt vmcnt(0)" ::: "memory");
;         } else {
;             XB_SPIN(xb_ld(&bar[XB_XGEN(b.x)]) == gen, bar);
.LBB0_28:
	s_or_b64 exec, exec, s[4:5]
	v_cvt_f32_u32_e32 v6, v4
	s_waitcnt vmcnt(0)
	v_readfirstlane_b32 s4, v5
	v_sub_u32_e32 v5, 0, v4
	v_rcp_iflag_f32_e32 v6, v6
	v_add_u32_e32 v7, s4, v3
	v_mul_f32_e32 v6, 0x4f7ffffe, v6
	v_cvt_u32_f32_e32 v6, v6
	v_mul_lo_u32 v3, v5, v6
	v_mul_hi_u32 v3, v6, v3
	v_add_u32_e32 v3, v6, v3
	v_mul_hi_u32 v3, v7, v3
	v_mul_lo_u32 v5, v3, v4
	v_sub_u32_e32 v5, v7, v5
	v_add_u32_e32 v6, 1, v3
	v_cmp_ge_u32_e32 vcc, v5, v4
	s_nop 1
	v_cndmask_b32_e32 v3, v3, v6, vcc
	v_sub_u32_e32 v6, v5, v4
	v_cndmask_b32_e32 v5, v5, v6, vcc
	v_add_u32_e32 v6, 1, v3
	v_cmp_ge_u32_e32 vcc, v5, v4
	v_add_u32_e32 v5, 1, v7
	s_nop 0
	v_cndmask_b32_e32 v3, v3, v6, vcc
	v_mul_lo_u32 v6, v4, v3
	v_add_u32_e32 v4, v6, v4
	v_cmp_ne_u32_e32 vcc, v5, v4
	s_and_saveexec_b64 s[4:5], vcc
	s_xor_b64 s[4:5], exec, s[4:5]
	s_cbranch_execz .LBB0_42
	v_readlane_b32 s28, v252, 26
	v_readlane_b32 s29, v252, 27
	s_and_b32 s99, s97, 15
	s_lshl_b32 s99, s99, 8
	s_add_u32 s28, s28, s99
	s_addc_u32 s29, s29, 0
	s_add_u32 s28, s28, 0xfffff000
	s_addc_u32 s29, s29, -1
	s_waitcnt lgkmcnt(0)
	s_nop 3
	global_load_dword v2, v207, s[28:29] sc1
	s_waitcnt vmcnt(0)
	v_cmp_eq_u32_e32 vcc, v2, v3
	s_and_saveexec_b64 s[36:37], vcc
	s_cbranch_execz .LBB0_41
	s_mov_b32 s34, 1
	s_mov_b64 s[38:39], 0
	s_branch .LBB0_32

; __device__ __forceinline__ unsigned xb_ld(unsigned* p)              { return __hip_atomic_load(p, __ATOMIC_RELAXED, __HIP_MEMORY_SCOPE_AGENT); }
; #define XB_SPIN(cond, bar) do { unsigned _sp = 0; while (cond) { __builtin_amdgcn_s_sleep(1); \
;     if ((++_sp & 255u) == 0u) { if (xb_ld(&(bar)[XB_TMO])) break; if (_sp > XB_SPIN_CAP) { atomicAdd(&(bar)[XB_TMO], 1u); break; } } } } while (0)
; __device__ __forceinline__ void xcd_barrier(const XcdBarrier& b) {
;     ...
;             XB_SPIN(xb_ld(&bar[XB_XGEN(b.x)]) == gen, bar);
.LBB0_34:
	v_readlane_b32 s28, v252, 26
	v_readlane_b32 s29, v252, 27
	s_and_b32 s99, s97, 15
	s_lshl_b32 s99, s99, 8
	s_add_u32 s28, s28, s99
	s_addc_u32 s29, s29, 0
	s_add_u32 s28, s28, 0xfffff000
	s_addc_u32 s29, s29, -1
	s_add_i32 s34, s34, 1
	s_mov_b64 s[44:45], -1
	s_nop 2
	global_load_dword v2, v207, s[28:29] sc1
	s_waitcnt vmcnt(0)
	v_cmp_ne_u32_e32 vcc, v2, v3
	s_orn2_b64 s[42:43], vcc, exec
	s_branch .LBB0_31

; __device__ __forceinline__ unsigned xb_ld(unsigned* p)              { return __hip_atomic_load(p, __ATOMIC_RELAXED, __HIP_MEMORY_SCOPE_AGENT); }
; __device__ __forceinline__ unsigned xb_add(unsigned* p, unsigned v) { return __hip_atomic_fetch_add(p, v, __ATOMIC_RELAXED, __HIP_MEMORY_SCOPE_AGENT); }
; #define XB_SPIN(cond, bar) do { unsigned _sp = 0; while (cond) { __builtin_amdgcn_s_sleep(1); \
;     if ((++_sp & 255u) == 0u) { if (xb_ld(&(bar)[XB_TMO])) break; if (_sp > XB_SPIN_CAP) { atomicAdd(&(bar)[XB_TMO], 1u); break; } } } } while (0)
; __device__ __forceinline__ void xcd_barrier(const XcdBarrier& b) {
;     ...
;             else XB_SPIN(xb_ld(&bar[XB_TOPGEN]) == tg, bar);
;             __builtin_amdgcn_fence(__ATOMIC_ACQUIRE, "agent");
;             xb_add(&bar[XB_XGEN(b.x)], 1u);
;             asm volatile("s_waitcnt vmcnt(0)" ::: "memory");
;         } else {
;             XB_SPIN(xb_ld(&bar[XB_XGEN(b.x)]) == gen, bar);
.Lxb_notlast_0:
	v_mov_b32_e32 v4, s98
	v_readlane_b32 s28, v252, 26
	v_readlane_b32 s29, v252, 27
	s_and_b32 s99, s97, 15
	s_lshl_b32 s99, s99, 8
	s_add_u32 s28, s28, s99
	s_addc_u32 s29, s29, 0
	s_add_u32 s28, s28, 0xfffff000
	s_addc_u32 s29, s29, -1
	s_mov_b64 s[38:39], 0
	s_nop 3
	global_load_dword v2, v207, s[28:29] sc1
	s_waitcnt vmcnt(0)
	v_cmp_eq_u32_e32 vcc, v2, v4
	s_and_saveexec_b64 s[36:37], vcc
	s_cbranch_execz .LBB0_56
	s_mov_b32 s34, 1
	s_branch .LBB0_49

; __device__ __forceinline__ unsigned xb_ld(unsigned* p)              { return __hip_atomic_load(p, __ATOMIC_RELAXED, __HIP_MEMORY_SCOPE_AGENT); }
; #define XB_SPIN(cond, bar) do { unsigned _sp = 0; while (cond) { __builtin_amdgcn_s_sleep(1); \
;     if ((++_sp & 255u) == 0u) { if (xb_ld(&(bar)[XB_TMO])) break; if (_sp > XB_SPIN_CAP) { atomicAdd(&(bar)[XB_TMO], 1u); break; } } } } while (0)
; __device__ __forceinline__ void xcd_barrier(const XcdBarrier& b) {
;     ...
;             else XB_SPIN(xb_ld(&bar[XB_TOPGEN]) == tg, bar);
.LBB0_51:
	v_readlane_b32 s28, v252, 26
	v_readlane_b32 s29, v252, 27
	s_and_b32 s99, s97, 15
	s_lshl_b32 s99, s99, 8
	s_add_u32 s28, s28, s99
	s_addc_u32 s29, s29, 0
	s_add_u32 s28, s28, 0xfffff000
	s_addc_u32 s29, s29, -1
	s_add_i32 s34, s34, 1
	s_mov_b64 s[44:45], -1
	s_nop 2
	global_load_dword v2, v207, s[28:29] sc1
	s_waitcnt vmcnt(0)
	v_cmp_ne_u32_e32 vcc, v2, v4
	s_orn2_b64 s[42:43], vcc, exec
	s_branch .LBB0_48

; __device__ __forceinline__ unsigned xb_ld(unsigned* p)              { return __hip_atomic_load(p, __ATOMIC_RELAXED, __HIP_MEMORY_SCOPE_AGENT); }
; __device__ __forceinline__ unsigned xb_add(unsigned* p, unsigned v) { return __hip_atomic_fetch_add(p, v, __ATOMIC_RELAXED, __HIP_MEMORY_SCOPE_AGENT); }
; #define XB_SPIN(cond, bar) do { unsigned _sp = 0; while (cond) { __builtin_amdgcn_s_sleep(1); \
;     if ((++_sp & 255u) == 0u) { if (xb_ld(&(bar)[XB_TMO])) break; if (_sp > XB_SPIN_CAP) { atomicAdd(&(bar)[XB_TMO], 1u); break; } } } } while (0)
; __device__ __forceinline__ void xcd_barrier(const XcdBarrier& b) {
;     ...
;         const unsigned old = xb_add(&bar[XB_XSUB(b.x)], 1u);
;         const unsigned gen = old / nloc;
;         if (old + 1u == (gen + 1u) * nloc) {
;             __builtin_amdgcn_fence(__ATOMIC_RELEASE, "agent");
;             asm volatile("s_waitcnt vmcnt(0)" ::: "memory");
;             const unsigned og = xb_add(&bar[XB_TOP], 1u);
;             const unsigned tg = og / nx;
;             if (og + 1u == (tg + 1u) * nx) xb_add(&bar[XB_TOPGEN], 1u);
;             else XB_SPIN(xb_ld(&bar[XB_TOPGEN]) == tg, bar);
;             __builtin_amdgcn_fence(__ATOMIC_ACQUIRE, "agent");
;             xb_add(&bar[XB_XGEN(b.x)], 1u);
;             asm volatile("s_waitcnt vmcnt(0)" ::: "memory");
;         } else {
;             XB_SPIN(xb_ld(&bar[XB_XGEN(b.x)]) == gen, bar);
.LBB0_307:
	s_or_b64 exec, exec, s[4:5]
	v_cvt_f32_u32_e32 v6, v4
	s_waitcnt vmcnt(0)
	v_readfirstlane_b32 s4, v5
	v_sub_u32_e32 v5, 0, v4
	v_rcp_iflag_f32_e32 v6, v6
	v_add_u32_e32 v7, s4, v3
	v_mul_f32_e32 v6, 0x4f7ffffe, v6
	v_cvt_u32_f32_e32 v6, v6
	v_mul_lo_u32 v3, v5, v6
	v_mul_hi_u32 v3, v6, v3
	v_add_u32_e32 v3, v6, v3
	v_mul_hi_u32 v3, v7, v3
	v_mul_lo_u32 v5, v3, v4
	v_sub_u32_e32 v5, v7, v5
	v_add_u32_e32 v6, 1, v3
	v_cmp_ge_u32_e32 vcc, v5, v4
	s_nop 1
	v_cndmask_b32_e32 v3, v3, v6, vcc
	v_sub_u32_e32 v6, v5, v4
	v_cndmask_b32_e32 v5, v5, v6, vcc
	v_add_u32_e32 v6, 1, v3
	v_cmp_ge_u32_e32 vcc, v5, v4
	v_add_u32_e32 v5, 1, v7
	s_nop 0
	v_cndmask_b32_e32 v3, v3, v6, vcc
	v_mul_lo_u32 v6, v4, v3
	v_add_u32_e32 v4, v6, v4
	v_cmp_ne_u32_e32 vcc, v5, v4
	s_and_saveexec_b64 s[4:5], vcc
	s_xor_b64 s[4:5], exec, s[4:5]
	s_cbranch_execz .LBB0_321
	v_readlane_b32 s28, v252, 26
	v_readlane_b32 s29, v252, 27
	s_and_b32 s99, s97, 15
	s_lshl_b32 s99, s99, 8
	s_add_u32 s28, s28, s99
	s_addc_u32 s29, s29, 0
	s_add_u32 s28, s28, 0xfffff000
	s_addc_u32 s29, s29, -1
	s_waitcnt lgkmcnt(0)
	s_nop 3
	global_load_dword v2, v207, s[28:29] sc1
	s_waitcnt vmcnt(0)
	v_cmp_eq_u32_e32 vcc, v2, v3
	s_and_saveexec_b64 s[38:39], vcc
	s_cbranch_execz .LBB0_320
	s_mov_b32 s34, 1
	s_mov_b64 s[40:41], 0
	s_branch .LBB0_311

; __device__ __forceinline__ unsigned xb_ld(unsigned* p)              { return __hip_atomic_load(p, __ATOMIC_RELAXED, __HIP_MEMORY_SCOPE_AGENT); }
; #define XB_SPIN(cond, bar) do { unsigned _sp = 0; while (cond) { __builtin_amdgcn_s_sleep(1); \
;     if ((++_sp & 255u) == 0u) { if (xb_ld(&(bar)[XB_TMO])) break; if (_sp > XB_SPIN_CAP) { atomicAdd(&(bar)[XB_TMO], 1u); break; } } } } while (0)
; __device__ __forceinline__ void xcd_barrier(const XcdBarrier& b) {
;     ...
;             XB_SPIN(xb_ld(&bar[XB_XGEN(b.x)]) == gen, bar);
.LBB0_313:
	v_readlane_b32 s28, v252, 26
	v_readlane_b32 s29, v252, 27
	s_and_b32 s99, s97, 15
	s_lshl_b32 s99, s99, 8
	s_add_u32 s28, s28, s99
	s_addc_u32 s29, s29, 0
	s_add_u32 s28, s28, 0xfffff000
	s_addc_u32 s29, s29, -1
	s_add_i32 s34, s34, 1
	s_mov_b64 s[48:49], -1
	s_nop 2
	global_load_dword v2, v207, s[28:29] sc1
	s_waitcnt vmcnt(0)
	v_cmp_ne_u32_e32 vcc, v2, v3
	s_orn2_b64 s[46:47], vcc, exec
	s_branch .LBB0_310

; __device__ __forceinline__ unsigned xb_ld(unsigned* p)              { return __hip_atomic_load(p, __ATOMIC_RELAXED, __HIP_MEMORY_SCOPE_AGENT); }
; __device__ __forceinline__ unsigned xb_add(unsigned* p, unsigned v) { return __hip_atomic_fetch_add(p, v, __ATOMIC_RELAXED, __HIP_MEMORY_SCOPE_AGENT); }
; #define XB_SPIN(cond, bar) do { unsigned _sp = 0; while (cond) { __builtin_amdgcn_s_sleep(1); \
;     if ((++_sp & 255u) == 0u) { if (xb_ld(&(bar)[XB_TMO])) break; if (_sp > XB_SPIN_CAP) { atomicAdd(&(bar)[XB_TMO], 1u); break; } } } } while (0)
; __device__ __forceinline__ void xcd_barrier(const XcdBarrier& b) {
;     ...
;             else XB_SPIN(xb_ld(&bar[XB_TOPGEN]) == tg, bar);
;             __builtin_amdgcn_fence(__ATOMIC_ACQUIRE, "agent");
;             xb_add(&bar[XB_XGEN(b.x)], 1u);
;             asm volatile("s_waitcnt vmcnt(0)" ::: "memory");
;         } else {
;             XB_SPIN(xb_ld(&bar[XB_XGEN(b.x)]) == gen, bar);
.Lxb_notlast_1:
	v_mov_b32_e32 v4, s98
	v_readlane_b32 s28, v252, 26
	v_readlane_b32 s29, v252, 27
	s_and_b32 s99, s97, 15
	s_lshl_b32 s99, s99, 8
	s_add_u32 s28, s28, s99
	s_addc_u32 s29, s29, 0
	s_add_u32 s28, s28, 0xfffff000
	s_addc_u32 s29, s29, -1
	s_mov_b64 s[40:41], 0
	s_nop 3
	global_load_dword v2, v207, s[28:29] sc1
	s_waitcnt vmcnt(0)
	v_cmp_eq_u32_e32 vcc, v2, v4
	s_and_saveexec_b64 s[38:39], vcc
	s_cbranch_execz .LBB0_335
	s_mov_b32 s34, 1
	s_branch .LBB0_328

; __device__ __forceinline__ unsigned xb_ld(unsigned* p)              { return __hip_atomic_load(p, __ATOMIC_RELAXED, __HIP_MEMORY_SCOPE_AGENT); }
; #define XB_SPIN(cond, bar) do { unsigned _sp = 0; while (cond) { __builtin_amdgcn_s_sleep(1); \
;     if ((++_sp & 255u) == 0u) { if (xb_ld(&(bar)[XB_TMO])) break; if (_sp > XB_SPIN_CAP) { atomicAdd(&(bar)[XB_TMO], 1u); break; } } } } while (0)
; __device__ __forceinline__ void xcd_barrier(const XcdBarrier& b) {
;     ...
;             else XB_SPIN(xb_ld(&bar[XB_TOPGEN]) == tg, bar);
.LBB0_330:
	v_readlane_b32 s28, v252, 26
	v_readlane_b32 s29, v252, 27
	s_and_b32 s99, s97, 15
	s_lshl_b32 s99, s99, 8
	s_add_u32 s28, s28, s99
	s_addc_u32 s29, s29, 0
	s_add_u32 s28, s28, 0xfffff000
	s_addc_u32 s29, s29, -1
	s_add_i32 s34, s34, 1
	s_mov_b64 s[48:49], -1
	s_nop 2
	global_load_dword v2, v207, s[28:29] sc1
	s_waitcnt vmcnt(0)
	v_cmp_ne_u32_e32 vcc, v2, v4
	s_orn2_b64 s[46:47], vcc, exec
	s_branch .LBB0_327
